# V tiles: transposed acc + permlane32_swap -> dwordx4 (64B/row) V^T stores; nop drop; preamble burst
# speedup vs baseline: 1.0056x; 1.0024x over previous
; __device__ __forceinline__ unsigned f2bf(float f) { unsigned u = __builtin_bit_cast(unsigned, f); return (u + 0x7fffu + ((u >> 16) & 1u)) >> 16; }
;     __device__ __forceinline__ void operator()(const f32x4 (&acc)[2][2][4][2], const pg8::Unit& u, int wr, int wc, int fr, int fq) const {
;     ...
;         } else if (pn < 6) {
;             const int head = 4 * (pn & 1) + wc, b = u.pm >> 3;
;             bf16_t* vb = Vt + (size_t)((b * 8 + head) * 64) * S_;
; #pragma unroll
;             for (int ai = 0; ai < 2; ++ai)
; #pragma unroll
;                 for (int m = 0; m < 4; ++m) { const int t = (row0 + ai * 128 + m * 16) & (S_ - 1);
;                     const int tp = (t & ~15) | (((t >> 2) & 1) << 3) | (((t >> 3) & 1) << 2) | (t & 3);
; #pragma unroll
;                     for (int bj = 0; bj < 2; ++bj)
; #pragma unroll
;                         for (int n = 0; n < 2; ++n) { const f32x4 a = acc[ai][bj][m][n]; const int d = 32 * bj + 8 * fq + 4 * n;
;                             vb[(unsigned)((d + 0) * S_ + tp)] = (bf16_t)f2bf(a.x); vb[(unsigned)((d + 1) * S_ + tp)] = (bf16_t)f2bf(a.y);
;                             vb[(unsigned)((d + 2) * S_ + tp)] = (bf16_t)f2bf(a.z); vb[(unsigned)((d + 3) * S_ + tp)] = (bf16_t)f2bf(a.w); }
;                 }
.LBB0_286:
	s_andn2_b64 vcc, exec, s[14:15]
	s_cbranch_vccnz .LBB0_288
	s_lshl_b32 s0, s21, 2
	s_and_b32 s0, s0, 4
	s_and_b32 s1, s20, 0x3fffff8
	s_or_b32 s0, s1, s0
	s_or_b32 s0, s0, s67
	s_lshl_b32 s14, s0, 6
	s_ashr_i32 s15, s14, 31
	s_lshl_b64 s[14:15], s[14:15], 12
	s_add_u32 s14, s65, s14
	s_addc_u32 s15, s66, s15
	s_and_b32 s0, s43, 0x7c0
	s_lshl_b32 s0, s0, 1
	v_and_b32_e32 v136, 12, v208
	v_and_b32_e32 v147, 3, v208
	v_lshlrev_b32_e32 v136, 13, v136
	v_lshl_or_b32 v136, v147, 12, v136
	v_bfe_u32 v147, v208, 4, 1
	v_lshl_or_b32 v136, v147, 4, v136
	v_bfe_u32 v147, v208, 5, 1
	v_lshl_or_b32 v136, v147, 5, v136
	v_add_u32_e32 v136, s0, v136
	v_add_u32_e32 v148, 0x4000, v136
	v_add_u32_e32 v149, 0x20000, v136
	v_add_u32_e32 v150, 0x24000, v136
	v_cvt_pk_bf16_f32 v178, v124, v125
	v_cvt_pk_bf16_f32 v179, v126, v127
	v_cvt_pk_bf16_f32 v180, v112, v113
	v_cvt_pk_bf16_f32 v181, v114, v115
	s_nop 1
	v_permlane32_swap_b32_e32 v178, v180
	v_permlane32_swap_b32_e32 v179, v181
	global_store_dwordx4 v136, v[178:181], s[14:15]
	v_cvt_pk_bf16_f32 v182, v120, v121
	v_cvt_pk_bf16_f32 v183, v122, v123
	v_cvt_pk_bf16_f32 v184, v104, v105
	v_cvt_pk_bf16_f32 v185, v106, v107
	s_nop 1
	v_permlane32_swap_b32_e32 v182, v184
	v_permlane32_swap_b32_e32 v183, v185
	global_store_dwordx4 v148, v[182:185], s[14:15]
	v_cvt_pk_bf16_f32 v186, v116, v117
	v_cvt_pk_bf16_f32 v187, v118, v119
	v_cvt_pk_bf16_f32 v188, v100, v101
	v_cvt_pk_bf16_f32 v189, v102, v103
	s_nop 1
	v_permlane32_swap_b32_e32 v186, v188
	v_permlane32_swap_b32_e32 v187, v189
	global_store_dwordx4 v149, v[186:189], s[14:15]
	v_cvt_pk_bf16_f32 v190, v108, v109
	v_cvt_pk_bf16_f32 v191, v110, v111
	v_cvt_pk_bf16_f32 v192, v92, v93
	v_cvt_pk_bf16_f32 v193, v94, v95
	s_nop 1
	v_permlane32_swap_b32_e32 v190, v192
	v_permlane32_swap_b32_e32 v191, v193
	global_store_dwordx4 v150, v[190:193], s[14:15]
	v_cvt_pk_bf16_f32 v198, v96, v97
	v_cvt_pk_bf16_f32 v199, v98, v99
	v_cvt_pk_bf16_f32 v200, v80, v81
	v_cvt_pk_bf16_f32 v201, v82, v83
	s_nop 1
	v_permlane32_swap_b32_e32 v198, v200
	v_permlane32_swap_b32_e32 v199, v201
	global_store_dwordx4 v136, v[198:201], s[14:15] offset:64
	v_cvt_pk_bf16_f32 v178, v88, v89
	v_cvt_pk_bf16_f32 v179, v90, v91
	v_cvt_pk_bf16_f32 v180, v72, v73
	v_cvt_pk_bf16_f32 v181, v74, v75
	s_nop 1
	v_permlane32_swap_b32_e32 v178, v180
	v_permlane32_swap_b32_e32 v179, v181
	global_store_dwordx4 v148, v[178:181], s[14:15] offset:64
	v_cvt_pk_bf16_f32 v182, v84, v85
	v_cvt_pk_bf16_f32 v183, v86, v87
	v_cvt_pk_bf16_f32 v184, v68, v69
	v_cvt_pk_bf16_f32 v185, v70, v71
	s_nop 1
	v_permlane32_swap_b32_e32 v182, v184
	v_permlane32_swap_b32_e32 v183, v185
	global_store_dwordx4 v149, v[182:185], s[14:15] offset:64
	v_cvt_pk_bf16_f32 v186, v76, v77
	v_cvt_pk_bf16_f32 v187, v78, v79
	v_cvt_pk_bf16_f32 v188, v64, v65
	v_cvt_pk_bf16_f32 v189, v66, v67
	s_nop 1
	v_permlane32_swap_b32_e32 v186, v188
	v_permlane32_swap_b32_e32 v187, v189
	global_store_dwordx4 v150, v[186:189], s[14:15] offset:64
	v_cvt_pk_bf16_f32 v190, v60, v61
	v_cvt_pk_bf16_f32 v191, v62, v63
	v_cvt_pk_bf16_f32 v192, v48, v49
	v_cvt_pk_bf16_f32 v193, v50, v51
	s_nop 1
	v_permlane32_swap_b32_e32 v190, v192
	v_permlane32_swap_b32_e32 v191, v193
	global_store_dwordx4 v136, v[190:193], s[14:15] offset:256
	v_cvt_pk_bf16_f32 v198, v56, v57
	v_cvt_pk_bf16_f32 v199, v58, v59
	v_cvt_pk_bf16_f32 v200, v40, v41
	v_cvt_pk_bf16_f32 v201, v42, v43
	s_nop 1
	v_permlane32_swap_b32_e32 v198, v200
	v_permlane32_swap_b32_e32 v199, v201
	global_store_dwordx4 v148, v[198:201], s[14:15] offset:256
	v_cvt_pk_bf16_f32 v178, v52, v53
	v_cvt_pk_bf16_f32 v179, v54, v55
	v_cvt_pk_bf16_f32 v180, v36, v37
	v_cvt_pk_bf16_f32 v181, v38, v39
	s_nop 1
	v_permlane32_swap_b32_e32 v178, v180
	v_permlane32_swap_b32_e32 v179, v181
	global_store_dwordx4 v149, v[178:181], s[14:15] offset:256
	v_cvt_pk_bf16_f32 v182, v44, v45
	v_cvt_pk_bf16_f32 v183, v46, v47
	v_cvt_pk_bf16_f32 v184, v28, v29
	v_cvt_pk_bf16_f32 v185, v30, v31
	s_nop 1
	v_permlane32_swap_b32_e32 v182, v184
	v_permlane32_swap_b32_e32 v183, v185
	global_store_dwordx4 v150, v[182:185], s[14:15] offset:256
	v_cvt_pk_bf16_f32 v186, v32, v33
	v_cvt_pk_bf16_f32 v187, v34, v35
	v_cvt_pk_bf16_f32 v188, v16, v17
	v_cvt_pk_bf16_f32 v189, v18, v19
	s_nop 1
	v_permlane32_swap_b32_e32 v186, v188
	v_permlane32_swap_b32_e32 v187, v189
	global_store_dwordx4 v136, v[186:189], s[14:15] offset:320
	v_cvt_pk_bf16_f32 v190, v24, v25
	v_cvt_pk_bf16_f32 v191, v26, v27
	v_cvt_pk_bf16_f32 v192, v8, v9
	v_cvt_pk_bf16_f32 v193, v10, v11
	s_nop 1
	v_permlane32_swap_b32_e32 v190, v192
	v_permlane32_swap_b32_e32 v191, v193
	global_store_dwordx4 v148, v[190:193], s[14:15] offset:320
	v_cvt_pk_bf16_f32 v198, v20, v21
	v_cvt_pk_bf16_f32 v199, v22, v23
	v_cvt_pk_bf16_f32 v200, v4, v5
	v_cvt_pk_bf16_f32 v201, v6, v7
	s_nop 1
	v_permlane32_swap_b32_e32 v198, v200
	v_permlane32_swap_b32_e32 v199, v201
	global_store_dwordx4 v149, v[198:201], s[14:15] offset:320
	v_cvt_pk_bf16_f32 v178, v12, v13
	v_cvt_pk_bf16_f32 v179, v14, v15
	v_cvt_pk_bf16_f32 v180, v0, v1
	v_cvt_pk_bf16_f32 v181, v2, v3
	s_nop 1
	v_permlane32_swap_b32_e32 v178, v180
	v_permlane32_swap_b32_e32 v179, v181
	global_store_dwordx4 v150, v[178:181], s[14:15] offset:320
